# P4 epilogue: row sum-of-squares loads prefetched in the unit preheader; epilogue no longer drains vmcnt(0)
# baseline (speedup 1.0000x reference)
; template <class Epi, class Sched, bool ALIGN_EPI = false, bool SP2 = false>
; __device__ __forceinline__ void gemm_phase(PG8_LAS unsigned char* lds, const Gemm g, const Sched& S, const Epi& E, const int wave_) {
;     ...
; #pragma unroll
;         for (int a = 0; a < 2; ++a)
; #pragma unroll
;             for (int b = 0; b < 2; ++b)
; #pragma unroll
;                 for (int m = 0; m < 4; ++m)
; #pragma unroll
;                     for (int n = 0; n < 2; ++n) acc[a][b][m][n] = (f32x4){0.f, 0.f, 0.f, 0.f};
;     __device__ __forceinline__ void operator()(const f32x4 (&acc)[2][2][4][2], const Unit& u, int wr, int wc, int fr, int fq) const {
;     ...
;         float ssr[2][4];
; #pragma unroll
;         for (int ai = 0; ai < 2; ++ai)
; #pragma unroll
;             for (int m = 0; m < 4; ++m) ssr[ai][m] = hss[row0 + ai * HALF + m * 16];
.LBB0_494:
	v_lshl_add_u32 v244, s4, 8, v153
	v_ashrrev_i32_e32 v245, 31, v244
	v_lshl_add_u64 v[246:247], v[244:245], 2, s[8:9]
	global_load_dword v236, v[246:247], off
	global_load_dword v237, v[246:247], off offset:64
	global_load_dword v238, v[246:247], off offset:128
	global_load_dword v239, v[246:247], off offset:192
	global_load_dword v240, v[246:247], off offset:512
	global_load_dword v241, v[246:247], off offset:576
	global_load_dword v242, v[246:247], off offset:640
	global_load_dword v243, v[246:247], off offset:704
	s_ashr_i32 s29, s28, 31
	s_lshl_b64 s[30:31], s[28:29], 20
	s_add_u32 s30, s38, s30
	s_addc_u32 s31, s39, s31
	s_and_b64 s[34:35], s[0:1], exec
	s_cselect_b32 s5, s31, s37
	s_cselect_b32 s7, s30, s36
	s_ashr_i32 s27, s26, 31
	s_lshl_b64 s[34:35], s[26:27], 20
	v_readlane_b32 s42, v248, 31
	v_readlane_b32 s43, v248, 32
	s_add_u32 s34, s42, s34
	s_addc_u32 s35, s43, s35
	s_and_b64 s[42:43], s[0:1], exec
	s_cselect_b32 s27, s35, s41
	s_cselect_b32 s29, s34, s40
	s_add_u32 s36, s36, 0x80080
	s_addc_u32 s37, s37, 0
	s_add_u32 s61, s40, 0x100
	v_mov_b32_e32 v0, 0
	s_addc_u32 s62, s41, 0
	s_mov_b32 s63, -2
	v_mov_b32_e32 v1, v0
	v_mov_b32_e32 v2, v0
	v_mov_b32_e32 v3, v0
	v_mov_b32_e32 v4, v0
	v_mov_b32_e32 v5, v0
	v_mov_b32_e32 v6, v0
	v_mov_b32_e32 v7, v0
	v_mov_b32_e32 v16, v0
	v_mov_b32_e32 v17, v0
	v_mov_b32_e32 v18, v0
	v_mov_b32_e32 v19, v0
	v_mov_b32_e32 v20, v0
	v_mov_b32_e32 v21, v0
	v_mov_b32_e32 v22, v0
	v_mov_b32_e32 v23, v0
	v_mov_b32_e32 v32, v0
	v_mov_b32_e32 v33, v0
	v_mov_b32_e32 v34, v0
	v_mov_b32_e32 v35, v0
	v_mov_b32_e32 v36, v0
	v_mov_b32_e32 v37, v0
	v_mov_b32_e32 v38, v0
	v_mov_b32_e32 v39, v0
	v_mov_b32_e32 v48, v0
	v_mov_b32_e32 v49, v0
	v_mov_b32_e32 v50, v0
	v_mov_b32_e32 v51, v0
	v_mov_b32_e32 v52, v0
	v_mov_b32_e32 v53, v0
	v_mov_b32_e32 v54, v0
	v_mov_b32_e32 v55, v0
	v_mov_b32_e32 v8, v0
	v_mov_b32_e32 v9, v0
	v_mov_b32_e32 v10, v0
	v_mov_b32_e32 v11, v0
	v_mov_b32_e32 v12, v0
	v_mov_b32_e32 v13, v0
	v_mov_b32_e32 v14, v0
	v_mov_b32_e32 v15, v0
	v_mov_b32_e32 v24, v0
	v_mov_b32_e32 v25, v0
	v_mov_b32_e32 v26, v0
	v_mov_b32_e32 v27, v0
	v_mov_b32_e32 v28, v0
	v_mov_b32_e32 v29, v0
	v_mov_b32_e32 v30, v0
	v_mov_b32_e32 v31, v0
	v_mov_b32_e32 v40, v0
	v_mov_b32_e32 v41, v0
	v_mov_b32_e32 v42, v0
	v_mov_b32_e32 v43, v0
	v_mov_b32_e32 v44, v0
	v_mov_b32_e32 v45, v0
	v_mov_b32_e32 v46, v0
	v_mov_b32_e32 v47, v0
	v_mov_b32_e32 v56, v0
	v_mov_b32_e32 v57, v0
	v_mov_b32_e32 v58, v0
	v_mov_b32_e32 v59, v0
	v_mov_b32_e32 v60, v0
	v_mov_b32_e32 v61, v0
	v_mov_b32_e32 v62, v0
	v_mov_b32_e32 v63, v0
	v_mov_b32_e32 v64, v0
	v_mov_b32_e32 v65, v0
	v_mov_b32_e32 v66, v0
	v_mov_b32_e32 v67, v0
	v_mov_b32_e32 v68, v0
	v_mov_b32_e32 v69, v0
	v_mov_b32_e32 v70, v0
	v_mov_b32_e32 v71, v0
	v_mov_b32_e32 v80, v0
	v_mov_b32_e32 v81, v0
	v_mov_b32_e32 v82, v0
	v_mov_b32_e32 v83, v0
	v_mov_b32_e32 v84, v0
	v_mov_b32_e32 v85, v0
	v_mov_b32_e32 v86, v0
	v_mov_b32_e32 v87, v0
	v_mov_b32_e32 v96, v0
	v_mov_b32_e32 v97, v0
	v_mov_b32_e32 v98, v0
	v_mov_b32_e32 v99, v0
	v_mov_b32_e32 v100, v0
	v_mov_b32_e32 v101, v0
	v_mov_b32_e32 v102, v0
	v_mov_b32_e32 v103, v0
	v_mov_b32_e32 v112, v0
	v_mov_b32_e32 v113, v0
	v_mov_b32_e32 v114, v0
	v_mov_b32_e32 v115, v0
	v_mov_b32_e32 v116, v0
	v_mov_b32_e32 v117, v0
	v_mov_b32_e32 v118, v0
	v_mov_b32_e32 v119, v0
	v_mov_b32_e32 v72, v0
	v_mov_b32_e32 v73, v0
	v_mov_b32_e32 v74, v0
	v_mov_b32_e32 v75, v0
	v_mov_b32_e32 v76, v0
	v_mov_b32_e32 v77, v0
	v_mov_b32_e32 v78, v0
	v_mov_b32_e32 v79, v0
	v_mov_b32_e32 v88, v0
	v_mov_b32_e32 v89, v0
	v_mov_b32_e32 v90, v0
	v_mov_b32_e32 v91, v0
	v_mov_b32_e32 v92, v0
	v_mov_b32_e32 v93, v0
	v_mov_b32_e32 v94, v0
	v_mov_b32_e32 v95, v0
	v_mov_b32_e32 v104, v0
	v_mov_b32_e32 v105, v0
	v_mov_b32_e32 v106, v0
	v_mov_b32_e32 v107, v0
	v_mov_b32_e32 v108, v0
	v_mov_b32_e32 v109, v0
	v_mov_b32_e32 v110, v0
	v_mov_b32_e32 v111, v0
	v_mov_b32_e32 v120, v0
	v_mov_b32_e32 v121, v0
	v_mov_b32_e32 v122, v0
	v_mov_b32_e32 v123, v0
	v_mov_b32_e32 v124, v0
	v_mov_b32_e32 v125, v0
	v_mov_b32_e32 v126, v0
	v_mov_b32_e32 v127, v0

; __device__ __forceinline__ unsigned cvt_pk_bf16(float lo, float hi) { unsigned r; asm volatile("v_cvt_pk_bf16_f32 %0, %1, %2" : "=v"(r) : "v"(lo), "v"(hi)); return r; }
; __device__ __forceinline__ float silu_f(float z) { return z * __builtin_amdgcn_rcpf(1.0f + __builtin_amdgcn_exp2f(-LOG2E * z)); }
;     __device__ __forceinline__ void operator()(const f32x4 (&acc)[2][2][4][2], const Unit& u, int wr, int wc, int fr, int fq) const {
;         const int region = u.pn >> 3, tl = u.pn & 7;
;         bf16_t* base = Q + (size_t)region * rstride;
;         const int row0 = u.pm * BM + wr * 64 + fr, col0 = tl * BM + wc * 32 + 8 * fq;
;         float ssr[2][4];
; #pragma unroll
;         for (int ai = 0; ai < 2; ++ai)
; #pragma unroll
;             for (int m = 0; m < 4; ++m) ssr[ai][m] = hss[row0 + ai * HALF + m * 16];
; #pragma unroll
;         for (int ai = 0; ai < 2; ++ai)
; #pragma unroll
;             for (int m = 0; m < 4; ++m) {
;                 const int row = row0 + ai * HALF + m * 16;
;                 float sc = __builtin_amdgcn_rsqf(ssr[ai][m] * (1.0f / DM) + EPS);
;                 if (region == 0) sc *= QSCALE;
;                 bf16_t* rowp = base + (size_t)row * DM + col0;
; #pragma unroll
;                 for (int bj = 0; bj < 2; ++bj) {
;                     f32x4 v0 = acc[ai][bj][m][0] * sc, v1 = acc[ai][bj][m][1] * sc;
;                     if (region == 3) {
; #pragma unroll
;                         for (int e = 0; e < 4; ++e) { v0[e] = silu_f(v0[e]); v1[e] = silu_f(v1[e]); }
;                     }
;                     u32x4 w; w.x = cvt_pk_bf16(v0[0], v0[1]); w.y = cvt_pk_bf16(v0[2], v0[3]); w.z = cvt_pk_bf16(v1[0], v1[1]); w.w = cvt_pk_bf16(v1[2], v1[3]);
;                     *(u32x4*)(rowp + bj * HALF) = w;
;                 }
.LBB0_498:
	v_lshl_add_u32 v146, s4, 8, v153
	v_ashrrev_i32_e32 v147, 31, v146
	v_mov_b32_e32 v136, v236
	v_or_b32_e32 v154, 16, v146
	v_or_b32_e32 v148, 48, v146
	v_ashrrev_i32_e32 v155, 31, v154
	v_or_b32_e32 v150, 32, v146
	v_ashrrev_i32_e32 v149, 31, v148
	v_ashrrev_i32_e32 v151, 31, v150
	v_mov_b32_e32 v174, v237
	v_mov_b32_e32 v173, v238
	v_mov_b32_e32 v172, v239
	v_mov_b32_e32 v171, v240
	v_mov_b32_e32 v170, v241
	v_mov_b32_e32 v169, v242
	v_mov_b32_e32 v168, v243
	s_ashr_i32 s40, s6, 3
	s_cmp_lt_u32 s6, 8
	s_cselect_b64 s[4:5], -1, 0
	s_cmp_eq_u32 s40, 3
	s_cselect_b64 s[36:37], -1, 0
	s_cmp_lg_u32 s40, 3
	s_waitcnt vmcnt(8)
	v_fmamk_f32 v136, v136, 0x3a000000, v167
	v_rsq_f32_e32 v136, v136
	s_nop 0
	v_mul_f32_e32 v156, 0x3e0293ee, v136
	v_cndmask_b32_e64 v156, v136, v156, s[4:5]
	v_pk_mul_f32 v[126:127], v[126:127], v[156:157] op_sel_hi:[1,0]
	v_pk_mul_f32 v[158:159], v[124:125], v[156:157] op_sel_hi:[1,0]
	v_pk_mul_f32 v[124:125], v[122:123], v[156:157] op_sel_hi:[1,0]
	v_pk_mul_f32 v[160:161], v[120:121], v[156:157] op_sel_hi:[1,0]
	s_cbranch_scc1 .LBB0_500
	v_mul_f32_e32 v136, 0xbfb8aa3b, v126
	v_mul_f32_e32 v121, 0xbfb8aa3b, v160
	v_exp_f32_e32 v136, v136
	v_mul_f32_e32 v157, 0xbfb8aa3b, v124
	v_mul_f32_e32 v122, 0xbfb8aa3b, v159
	v_exp_f32_e32 v121, v121
	v_exp_f32_e32 v157, v157
	v_exp_f32_e32 v123, v122
	v_add_f32_e32 v136, 1.0, v136
	v_add_f32_e32 v121, 1.0, v121
	v_rcp_f32_e32 v176, v136
	v_add_f32_e32 v136, 1.0, v157
	v_mul_f32_e32 v157, 0xbfb8aa3b, v127
	v_mul_f32_e32 v120, 0xbfb8aa3b, v158
	v_rcp_f32_e32 v122, v121
	v_add_f32_e32 v121, 1.0, v123
	v_mul_f32_e32 v123, 0xbfb8aa3b, v161
	v_exp_f32_e32 v157, v157
	v_mul_f32_e32 v175, 0xbfb8aa3b, v125
	v_exp_f32_e32 v120, v120
	v_exp_f32_e32 v123, v123
	v_exp_f32_e32 v175, v175
	v_rcp_f32_e32 v178, v136
	v_add_f32_e32 v136, 1.0, v157
	v_add_f32_e32 v120, 1.0, v120
	v_add_f32_e32 v123, 1.0, v123
	v_rcp_f32_e32 v177, v136
	v_add_f32_e32 v136, 1.0, v175
	v_rcp_f32_e32 v120, v120
	v_rcp_f32_e32 v121, v121
	v_rcp_f32_e32 v179, v136
	v_rcp_f32_e32 v123, v123
	v_pk_mul_f32 v[126:127], v[126:127], v[176:177]
	v_pk_mul_f32 v[158:159], v[158:159], v[120:121]
	v_pk_mul_f32 v[124:125], v[124:125], v[178:179]
	v_pk_mul_f32 v[160:161], v[160:161], v[122:123]
